# code placement: gates GEMM K-loop also moved to 0 mod 8 (attention and downstream GEMMs as in the previous version)
# speedup vs baseline: 1.0118x; 1.0016x over previous
;     __device__ bool next(int i, Unit& u) const { u.aoff = 0; return tile((long)i * G + c, u.pm, u.pn); }
; template <class Epi, class Sched, bool ALIGN_EPI>
; __device__ __forceinline__ void gemm_phase(LAS unsigned char* lds, const Gemm g, const Sched& S, const Epi& E) {
;     ...
;     for (;;) {
;         const bool has_next = S.next(ui + 1, nxt);
;         const char* nA = has_next ? (const char*)g.A + (size_t)nxt.pm * tstepA + nxt.aoff : cA; const char* nB = has_next ? (const char*)g.Bt + (size_t)nxt.pn * tstepB : cB;
;         for (int t = 0; t < nt; t += 2) {
.LBB0_297:
	s_nop 0
	s_mov_b64 s[14:15], 0
